# layer-0 mixer input weight conversion: next tile of the block touched ahead (distance by column tile, guarded)
# speedup vs baseline: 1.0064x; 1.0064x over previous
; __device__ __forceinline__ void cvt_matrix(const float* __restrict__ src, int ldsrc, int K, int Nsrc, int Npad,
;                                            u16* __restrict__ dst, int& ctr, float* tl, int tid, int bid, int G) {
;     ...
;   for (int t = first; t < T; t += G) {
;     const int k0 = (t / nn) * 64, n0 = (t % nn) * 64;
;     {
;       const int r = tid >> 4, c4 = (tid & 15) * 4;
; #pragma unroll
;       for (int i = 0; i < 2; ++i) {
;         const int rr = r + 32 * i;
;         float4 v = make_float4(0.f, 0.f, 0.f, 0.f);
;         if (n0 + c4 < Nsrc) v = *(const float4*)(src + (size_t)(k0 + rr) * ldsrc + n0 + c4);
;         float* d = tl + rr * 65 + c4;
;         d[0] = v.x; d[1] = v.y; d[2] = v.z; d[3] = v.w;
;       }
;     }
;     __syncthreads();
;     {
;       const int n = tid >> 3, k8 = (tid & 7) * 8;
;       float f[8];
; #pragma unroll
;       for (int i = 0; i < 8; ++i) f[i] = tl[(k8 + i) * 65 + n];
;       u32x4 w = {cvtpk(f[0], f[1]), cvtpk(f[2], f[3]), cvtpk(f[4], f[5]), cvtpk(f[6], f[7])};
;       *(u32x4*)(dst + (size_t)(n0 + n) * K + k0 + k8) = w;
;     }
;     __syncthreads();
.LBB0_774:
	s_or_b64 exec, exec, s[8:9]
	s_waitcnt vmcnt(3)
	ds_write2_b32 v16, v0, v1 offset1:1
	ds_write2_b32 v16, v2, v3 offset0:2 offset1:3
	v_add_u32_e32 v0, 0x2080, v16
	s_waitcnt vmcnt(2)
	ds_write2_b32 v0, v4, v5 offset1:1
	v_add_u32_e32 v0, 0x2088, v16
	ds_write2_b32 v0, v6, v7 offset1:1
	s_waitcnt lgkmcnt(0)
	s_barrier
	ds_read2_b32 v[0:1], v17 offset1:65
	ds_read2_b32 v[2:3], v17 offset0:130 offset1:195
	v_add_u32_e32 v6, 0x400, v17
	ds_read2_b32 v[4:5], v6 offset0:4 offset1:69
	ds_read2_b32 v[6:7], v6 offset0:134 offset1:199
	s_waitcnt lgkmcnt(3)
	v_cvt_pk_bf16_f32 v0, v0, v1
	s_waitcnt lgkmcnt(2)
	v_cvt_pk_bf16_f32 v1, v2, v3
	s_waitcnt lgkmcnt(1)
	v_cvt_pk_bf16_f32 v2, v4, v5
	v_add_u32_e32 v4, s6, v12
	v_ashrrev_i32_e32 v5, 31, v4
	v_readlane_b32 s6, v253, 7
	v_lshlrev_b64 v[4:5], 11, v[4:5]
	v_readlane_b32 s7, v253, 8
	s_ashr_i32 s5, s4, 31
	s_add_i32 s10, s10, s71
	v_lshl_add_u64 v[4:5], s[6:7], 0, v[4:5]
	v_lshl_add_u64 v[4:5], s[4:5], 1, v[4:5]
	s_add_i32 s11, s11, s16
	v_lshl_add_u64 v[4:5], v[4:5], 0, v[200:201]
	s_cmpk_lt_i32 s10, 0x340
	s_waitcnt lgkmcnt(0)
	v_cvt_pk_bf16_f32 v3, v6, v7
	global_store_dwordx4 v[4:5], v[0:3], off
	s_barrier
	s_cbranch_scc0 .LBB0_777
.LBB0_775:
	s_mul_hi_i32 s4, s10, 0x4ec4ec4f
	s_lshr_b32 s5, s4, 31
	s_ashr_i32 s4, s4, 4
	s_add_i32 s5, s4, s5
	s_lshl_b32 s4, s5, 6
	s_mulk_i32 s5, 0xf300
	s_add_i32 s6, s5, s11
	v_add_u32_e32 v0, s6, v15
	s_movk_i32 s5, 0xc20
	v_cmp_gt_i32_e32 vcc, s5, v0
	v_mov_b32_e32 v0, 0
	v_mov_b32_e32 v1, 0
	v_mov_b32_e32 v2, 0
	v_mov_b32_e32 v3, 0
	v_mov_b32_e32 v4, 0
	v_mov_b32_e32 v5, 0
	v_mov_b32_e32 v6, 0
	v_mov_b32_e32 v7, 0
	s_and_saveexec_b64 s[8:9], vcc
	s_cbranch_execz .LBB0_774
	s_ashr_i32 s7, s6, 31
	v_lshl_add_u64 v[0:1], s[6:7], 2, v[10:11]
	v_add_u32_e32 v4, s4, v9
	s_movk_i32 s5, 0x3080
	v_mad_i64_i32 v[2:3], s[18:19], v4, s5, v[0:1]
	v_add_u32_e32 v4, 32, v4
	v_mad_i64_i32 v[4:5], s[18:19], v4, s5, v[0:1]
	s_mov_b32 s18, 0x30b000
	s_mov_b32 s19, 0x3c9c00
	s_cmpk_lt_i32 s6, 0x100
	s_cselect_b32 s18, s18, s19
	s_cmpk_lt_i32 s10, 0x240
	s_cselect_b32 s18, s18, 0
	v_add_co_u32_e32 v18, vcc, s18, v2
	s_nop 1
	v_addc_co_u32_e32 v19, vcc, 0, v3, vcc
	v_add_co_u32_e32 v20, vcc, s18, v4
	s_nop 1
	v_addc_co_u32_e32 v21, vcc, 0, v5, vcc
	global_load_dwordx4 v[0:3], v[2:3], off
	s_nop 0
	global_load_dwordx4 v[4:7], v[4:5], off
	global_load_dword v248, v[18:19], off
	global_load_dword v249, v[20:21], off
	s_branch .LBB0_774
